# cmp_mlp_block staging loads issued together (17 in flight, counted vmcnt) instead of one load + vmcnt(0) per iteration
# speedup vs baseline: 1.0107x; 1.0022x over previous
; DI void cmp_mlp_block(const Params& p, int layer, int item, int wid, int lane) {
;     ...
;   {
;     const int tokb = b * S_ + 16 * c0;
;     for (int idx = wid * 64 + lane; idx < 528 * 16; idx += NTHREADS) {
;       const int r = idx >> 4, ch = idx & 15;
;       int tk = tokb + r; tk = tk > T_ - 1 ? T_ - 1 : tk;
;       const bf16x8 v = ldg8(proj + (size_t)tk * PS + ccol + ch * 8);
;       *reinterpret_cast<bf16x8*>(smem + ((r & 15) * 33 + (r >> 4)) * 272 + ch * 16) = v;
;     }
;   }
.LBB0_300:
	s_lshl_b32 s2, s12, 5
	s_bfe_u32 s13, s12, 0x10005
	s_bfe_u32 s14, s12, 0x20003
	s_and_b32 s16, s2, 0xe0
	s_cmp_lt_u32 s12, 64
	s_cselect_b64 s[8:9], -1, 0
	s_lshl_b32 s15, s14, 12
	s_and_saveexec_b64 s[2:3], s[0:1]
	s_cbranch_execz .LBB0_303
	s_lshl_b32 s10, s16, 4
	s_or_b32 s17, s15, s10
	s_and_b64 s[10:11], s[8:9], exec
	s_movk_i32 s10, 0x3400
	s_cselect_b32 s10, s10, 0x3600
	s_lshl_b32 s11, s13, 8
	s_or_b32 s10, s11, s10
	s_mov_b32 s11, s28
	v_lshl_add_u64 v[2:3], v[62:63], 0, s[10:11]
	s_mov_b64 s[10:11], 0
	v_ashrrev_i32_e32 v0, 4, v239
	v_add_u32_e32 v4, s17, v0
	v_min_i32_e32 v4, 0x3fff, v4
	v_mad_i64_i32 v[4:5], s[18:19], v4, s37, v[2:3]
	global_load_dwordx4 v[106:109], v[4:5], off
	s_add_i32 s10, s17, 32
	v_add_u32_e32 v4, s10, v0
	v_min_i32_e32 v4, 0x3fff, v4
	v_mad_i64_i32 v[4:5], s[18:19], v4, s37, v[2:3]
	global_load_dwordx4 v[110:113], v[4:5], off
	s_add_i32 s10, s17, 64
	v_add_u32_e32 v4, s10, v0
	v_min_i32_e32 v4, 0x3fff, v4
	v_mad_i64_i32 v[4:5], s[18:19], v4, s37, v[2:3]
	global_load_dwordx4 v[114:117], v[4:5], off
	s_add_i32 s10, s17, 96
	v_add_u32_e32 v4, s10, v0
	v_min_i32_e32 v4, 0x3fff, v4
	v_mad_i64_i32 v[4:5], s[18:19], v4, s37, v[2:3]
	global_load_dwordx4 v[118:121], v[4:5], off
	s_add_i32 s10, s17, 128
	v_add_u32_e32 v4, s10, v0
	v_min_i32_e32 v4, 0x3fff, v4
	v_mad_i64_i32 v[4:5], s[18:19], v4, s37, v[2:3]
	global_load_dwordx4 v[122:125], v[4:5], off
	s_add_i32 s10, s17, 160
	v_add_u32_e32 v4, s10, v0
	v_min_i32_e32 v4, 0x3fff, v4
	v_mad_i64_i32 v[4:5], s[18:19], v4, s37, v[2:3]
	global_load_dwordx4 v[126:129], v[4:5], off
	s_add_i32 s10, s17, 192
	v_add_u32_e32 v4, s10, v0
	v_min_i32_e32 v4, 0x3fff, v4
	v_mad_i64_i32 v[4:5], s[18:19], v4, s37, v[2:3]
	global_load_dwordx4 v[130:133], v[4:5], off
	s_add_i32 s10, s17, 224
	v_add_u32_e32 v4, s10, v0
	v_min_i32_e32 v4, 0x3fff, v4
	v_mad_i64_i32 v[4:5], s[18:19], v4, s37, v[2:3]
	global_load_dwordx4 v[134:137], v[4:5], off
	s_add_i32 s10, s17, 256
	v_add_u32_e32 v4, s10, v0
	v_min_i32_e32 v4, 0x3fff, v4
	v_mad_i64_i32 v[4:5], s[18:19], v4, s37, v[2:3]
	global_load_dwordx4 v[138:141], v[4:5], off
	s_add_i32 s10, s17, 288
	v_add_u32_e32 v4, s10, v0
	v_min_i32_e32 v4, 0x3fff, v4
	v_mad_i64_i32 v[4:5], s[18:19], v4, s37, v[2:3]
	global_load_dwordx4 v[142:145], v[4:5], off
	s_add_i32 s10, s17, 320
	v_add_u32_e32 v4, s10, v0
	v_min_i32_e32 v4, 0x3fff, v4
	v_mad_i64_i32 v[4:5], s[18:19], v4, s37, v[2:3]
	global_load_dwordx4 v[146:149], v[4:5], off
	s_add_i32 s10, s17, 352
	v_add_u32_e32 v4, s10, v0
	v_min_i32_e32 v4, 0x3fff, v4
	v_mad_i64_i32 v[4:5], s[18:19], v4, s37, v[2:3]
	global_load_dwordx4 v[150:153], v[4:5], off
	s_add_i32 s10, s17, 384
	v_add_u32_e32 v4, s10, v0
	v_min_i32_e32 v4, 0x3fff, v4
	v_mad_i64_i32 v[4:5], s[18:19], v4, s37, v[2:3]
	global_load_dwordx4 v[154:157], v[4:5], off
	s_add_i32 s10, s17, 416
	v_add_u32_e32 v4, s10, v0
	v_min_i32_e32 v4, 0x3fff, v4
	v_mad_i64_i32 v[4:5], s[18:19], v4, s37, v[2:3]
	global_load_dwordx4 v[158:161], v[4:5], off
	s_add_i32 s10, s17, 448
	v_add_u32_e32 v4, s10, v0
	v_min_i32_e32 v4, 0x3fff, v4
	v_mad_i64_i32 v[4:5], s[18:19], v4, s37, v[2:3]
	global_load_dwordx4 v[166:169], v[4:5], off
	s_add_i32 s10, s17, 480
	v_add_u32_e32 v4, s10, v0
	v_min_i32_e32 v4, 0x3fff, v4
	v_mad_i64_i32 v[4:5], s[18:19], v4, s37, v[2:3]
	global_load_dwordx4 v[170:173], v[4:5], off
	s_add_i32 s10, s17, 512
	v_add_u32_e32 v4, s10, v0
	v_min_i32_e32 v4, 0x3fff, v4
	v_mad_i64_i32 v[4:5], s[18:19], v4, s37, v[2:3]
	global_load_dwordx4 v[174:177], v[4:5], off
	v_and_b32_e32 v8, 15, v0
	v_ashrrev_i32_e32 v9, 8, v239
	v_mad_u32_u24 v8, v8, 33, v9
	v_mad_u32_u24 v8, v8, s38, v50
	v_readfirstlane_b32 s18, v164
	s_waitcnt vmcnt(16)
	ds_write_b128 v8, v[106:109]
	s_waitcnt vmcnt(15)
	ds_write_b128 v8, v[110:113] offset:544
	s_waitcnt vmcnt(14)
	ds_write_b128 v8, v[114:117] offset:1088
	s_waitcnt vmcnt(13)
	ds_write_b128 v8, v[118:121] offset:1632
	s_waitcnt vmcnt(12)
	ds_write_b128 v8, v[122:125] offset:2176
	s_waitcnt vmcnt(11)
	ds_write_b128 v8, v[126:129] offset:2720
	s_waitcnt vmcnt(10)
	ds_write_b128 v8, v[130:133] offset:3264
	s_waitcnt vmcnt(9)
	ds_write_b128 v8, v[134:137] offset:3808
	s_waitcnt vmcnt(8)
	ds_write_b128 v8, v[138:141] offset:4352
	s_waitcnt vmcnt(7)
	ds_write_b128 v8, v[142:145] offset:4896
	s_waitcnt vmcnt(6)
	ds_write_b128 v8, v[146:149] offset:5440
	s_waitcnt vmcnt(5)
	ds_write_b128 v8, v[150:153] offset:5984
	s_waitcnt vmcnt(4)
	ds_write_b128 v8, v[154:157] offset:6528
	s_waitcnt vmcnt(3)
	ds_write_b128 v8, v[158:161] offset:7072
	s_waitcnt vmcnt(2)
	ds_write_b128 v8, v[166:169] offset:7616
	s_waitcnt vmcnt(1)
	ds_write_b128 v8, v[170:173] offset:8160
	s_waitcnt vmcnt(0)
	s_cmp_lt_u32 s18, 4
	s_cbranch_scc0 .Lcm_st_done
	ds_write_b128 v8, v[174:177] offset:8704
; DI void cmp_mlp_block(const Params& p, int layer, int item, int wid, int lane) {
;     ...
;   const u16* w1t = (const u16*)(p.ws + (kv ? OFF_W1V_T : OFF_W1K_T));
;   const u16* w2t = (const u16*)(p.ws + (kv ? OFF_W2V_T : OFF_W2K_T));
;   const float* pos = (kv ? p.cpv : p.cpk) + (size_t)layer * 32 * 128;
;   const int ccol = (kv ? C_VC : C_KC) + g * 128;
;   f32x16 hacc = zero16();
;   {
;     const int tokb = b * S_ + 16 * c0;
;     for (int idx = wid * 64 + lane; idx < 528 * 16; idx += NTHREADS) {
;       const int r = idx >> 4, ch = idx & 15;
;       int tk = tokb + r; tk = tk > T_ - 1 ? T_ - 1 : tk;
;       const bf16x8 v = ldg8(proj + (size_t)tk * PS + ccol + ch * 8);
;       *reinterpret_cast<bf16x8*>(smem + ((r & 15) * 33 + (r >> 4)) * 272 + ch * 16) = v;
;     }
;   }
;   __syncthreads();
;   const u16* wfr = w1t + (size_t)wid * 256 * 64 * 8 + lane * 8;
; #pragma unroll 2
;   for (int l = 0; l < 32; ++l) {
;     bf16x8 wf[8];
; #pragma unroll
;     for (int s2 = 0; s2 < 8; ++s2) wf[s2] = ldg8(wfr + (size_t)(l * 8 + s2) * 64 * 8);
.Lcm_st_done:
.LBB0_303:
	s_or_b64 exec, exec, s[2:3]
	v_readlane_b32 s52, v254, 0
	s_and_b64 s[2:3], s[8:9], exec
	v_readlane_b32 s60, v254, 8
	v_readlane_b32 s62, v254, 10
	s_mov_b32 s2, 0x4300000
	v_readlane_b32 s61, v254, 9
	v_readlane_b32 s63, v254, 11
	s_cselect_b32 s10, s60, s62
	s_cselect_b32 s2, s2, 0x4500000
	s_cselect_b32 s11, s61, s63
	s_add_u32 s10, s10, s6
	s_mov_b32 s3, s28
	s_addc_u32 s11, s11, s7
	v_lshlrev_b32_e32 v0, 2, v52
	v_mov_b32_e32 v2, 0
	v_lshl_add_u64 v[68:69], s[10:11], 0, v[0:1]
	v_lshl_add_u64 v[70:71], v[64:65], 0, s[2:3]
	s_mov_b32 s2, 1
	s_mov_b64 s[10:11], 0
	v_mov_b32_e32 v3, v2
	v_mov_b32_e32 v4, v2
	v_mov_b32_e32 v5, v2
	v_mov_b32_e32 v6, v2
	v_mov_b32_e32 v7, v2
	v_mov_b32_e32 v8, v2
	v_mov_b32_e32 v9, v2
	v_mov_b32_e32 v10, v2
	v_mov_b32_e32 v11, v2
	v_mov_b32_e32 v12, v2
	v_mov_b32_e32 v13, v2
	v_mov_b32_e32 v14, v2
	v_mov_b32_e32 v15, v2
	v_mov_b32_e32 v16, v2
	v_mov_b32_e32 v17, v2
	v_readlane_b32 s53, v254, 1
	v_readlane_b32 s54, v254, 2
	v_readlane_b32 s55, v254, 3
	v_readlane_b32 s56, v254, 4
	v_readlane_b32 s57, v254, 5
	v_readlane_b32 s58, v254, 6
	v_readlane_b32 s59, v254, 7
	v_readlane_b32 s64, v254, 12
	v_readlane_b32 s65, v254, 13
	v_readlane_b32 s66, v254, 14
	v_readlane_b32 s67, v254, 15
	s_waitcnt lgkmcnt(0)
	s_barrier
	s_mov_b64 s[18:19], 0x2000
	v_add_co_u32_e32 v174, vcc, 0xffffc400, v70
	s_nop 1
	v_addc_co_u32_e32 v175, vcc, -1, v71, vcc
	v_add_co_u32_e32 v176, vcc, 0xffffd400, v70
	s_nop 1
	v_addc_co_u32_e32 v177, vcc, -1, v71, vcc
	v_mad_u32_u24 v75, v53, s38, v182
	v_lshl_add_u64 v[72:73], v[68:69], 0, s[10:11]
	s_mov_b32 s2, 0
	global_load_dwordx4 v[18:21], v[174:175], off
	global_load_dwordx4 v[106:109], v[72:73], off
	global_load_dwordx4 v[110:113], v[72:73], off offset:16
	global_load_dwordx4 v[22:25], v[174:175], off offset:1024
	global_load_dwordx4 v[114:117], v[72:73], off offset:64
	global_load_dwordx4 v[118:121], v[72:73], off offset:80
	global_load_dwordx4 v[26:29], v[174:175], off offset:2048
	global_load_dwordx4 v[122:125], v[72:73], off offset:128
	global_load_dwordx4 v[126:129], v[72:73], off offset:144
	global_load_dwordx4 v[30:33], v[174:175], off offset:3072
	global_load_dwordx4 v[130:133], v[72:73], off offset:192
	global_load_dwordx4 v[134:137], v[72:73], off offset:208
	global_load_dwordx4 v[34:37], v[176:177], off
	global_load_dwordx4 v[138:141], v[72:73], off offset:256
	global_load_dwordx4 v[142:145], v[72:73], off offset:272
	global_load_dwordx4 v[38:41], v[176:177], off offset:1024
	global_load_dwordx4 v[146:149], v[72:73], off offset:320
	global_load_dwordx4 v[150:153], v[72:73], off offset:336
	global_load_dwordx4 v[42:45], v[176:177], off offset:2048
	global_load_dwordx4 v[154:157], v[72:73], off offset:384
	global_load_dwordx4 v[158:161], v[72:73], off offset:400
	global_load_dwordx4 v[46:49], v[176:177], off offset:3072
	global_load_dwordx4 v[166:169], v[72:73], off offset:448
	global_load_dwordx4 v[170:173], v[72:73], off offset:464
	v_lshl_add_u64 v[174:175], v[174:175], 0, s[18:19]
	v_lshl_add_u64 v[176:177], v[176:177], 0, s[18:19]
	s_movk_i32 s10, 0x200
